# S5 pass B prologue: segment carry loads batched (7 in flight), carry recurrence unrolled with uniform exit
# speedup vs baseline: 1.0041x; 1.0013x over previous
; template <bool PASSB>
; DI void s5_pass(const int tid, LAS unsigned char* lds, const P& p, int G, int c0) {
;     ...
;         { const f32x4* bp = (const f32x4*)(bbar + ((size_t)(g * 64 + lane)) * 32);
; #pragma unroll
;           for (int k = 0; k < 4; ++k) { f32x4 v = bp[k]; bre[4 * k] = v[0]; bre[4 * k + 1] = v[1]; bre[4 * k + 2] = v[2]; bre[4 * k + 3] = v[3]; }
; #pragma unroll
;           for (int k = 0; k < 4; ++k) { f32x4 v = bp[4 + k]; bim[4 * k] = v[0]; bim[4 * k + 1] = v[1]; bim[4 * k + 2] = v[2]; bim[4 * k + 3] = v[3]; } }
;         const float are = abar[(g * 64 + lane) * 2], aim = abar[(g * 64 + lane) * 2 + 1];
;         float hre = 0.f, him = 0.f;
;         bf16x8 cf[4]; float dsk = 0.f;
;         if (PASSB) {
; #pragma unroll
;             for (int ks = 0; ks < 4; ++ks) cf[ks] = *(const bf16x8*)(ccat + ((size_t)(g * 16 + fr)) * 128 + ks * 32 + fq * 8);
;             dsk = dskip[g * 16 + fr];
;             float pr = are, pi = aim;
; #pragma unroll
;             for (int s = 0; s < 8; ++s) { const float nr = pr * pr - pi * pi, ni = 2.f * pr * pi; pr = nr; pi = ni; }
;             for (int s = 0; s < seg; ++s) { const float* he = hend + (((size_t)(b * 16 + g) * 8 + s) * 64 + lane) * 2; const float er = he[0], ei = he[1];
;                 const float nr = pr * hre - pi * him + er, ni = pr * him + pi * hre + ei; hre = nr; him = ni; }
;         }
.LBB0_568:
	s_ashr_i32 s1, s12, 5
	v_lshl_or_b32 v16, s1, 6, v76
	s_lshl_b32 s0, s12, 3
	v_ashrrev_i32_e32 v17, 31, v16
	v_readlane_b32 s8, v251, 31
	s_and_b32 s0, s0, 0xf8
	v_lshlrev_b64 v[0:1], 7, v[16:17]
	v_readlane_b32 s9, v251, 32
	v_add_u32_e32 v64, s0, v53
	v_lshlrev_b32_e32 v16, 1, v16
	v_lshl_add_u64 v[18:19], s[8:9], 0, v[0:1]
	v_readlane_b32 s8, v251, 29
	s_lshl_b32 s0, s1, 4
	global_load_dwordx4 v[0:3], v[18:19], off offset:48
	global_load_dwordx4 v[4:7], v[18:19], off offset:32
	global_load_dwordx4 v[8:11], v[18:19], off offset:16
	global_load_dwordx4 v[12:15], v[18:19], off
	global_load_dwordx4 v[44:47], v[18:19], off offset:112
	global_load_dwordx4 v[40:43], v[18:19], off offset:96
	global_load_dwordx4 v[32:35], v[18:19], off offset:80
	global_load_dwordx4 v[36:39], v[18:19], off offset:64
	v_ashrrev_i32_e32 v17, 31, v16
	v_readlane_b32 s9, v251, 30
	v_or_b32_e32 v62, s0, v149
	v_ashrrev_i32_e32 v63, 31, v62
	v_lshl_add_u64 v[16:17], v[16:17], 2, s[8:9]
	global_load_dwordx2 v[60:61], v[16:17], off
	v_lshlrev_b64 v[16:17], 8, v[62:63]
	v_lshl_add_u64 v[28:29], v[50:51], 0, v[16:17]
	v_readlane_b32 s60, v253, 52
	global_load_dwordx4 v[16:19], v[28:29], off
	global_load_dwordx4 v[20:23], v[28:29], off offset:64
	global_load_dwordx4 v[24:27], v[28:29], off offset:128
	s_nop 0
	global_load_dwordx4 v[28:31], v[28:29], off offset:192
	v_readlane_b32 s64, v253, 56
	v_readlane_b32 s65, v253, 57
	v_mov_b32_e32 v180, v181
	v_mov_b64_e32 v[74:75], v[180:181]
	v_lshl_add_u64 v[62:63], v[62:63], 2, s[64:65]
	global_load_dword v90, v[62:63], off
	v_ashrrev_i32_e32 v62, 3, v64
	v_readlane_b32 s61, v253, 53
	v_readlane_b32 s62, v253, 54
	v_readlane_b32 s63, v253, 55
	v_readlane_b32 s66, v253, 58
	v_readlane_b32 s67, v253, 59
	v_readlane_b32 s68, v253, 60
	v_readlane_b32 s69, v253, 61
	v_readlane_b32 s70, v253, 62
	v_readlane_b32 s71, v253, 63
	v_readlane_b32 s72, v254, 0
	v_readlane_b32 s73, v254, 1
	v_readlane_b32 s74, v254, 2
	v_readlane_b32 s75, v254, 3
	s_and_saveexec_b64 s[8:9], s[4:5]
	s_cbranch_execz .LBB0_572
	s_waitcnt vmcnt(0)
	v_pk_mul_f32 v[64:65], v[60:61], v[60:61]
	v_add_f32_e32 v63, v60, v60
	v_sub_f32_e32 v64, v64, v65
	v_mul_f32_e32 v63, v61, v63
	v_add_f32_e32 v65, v64, v64
	v_mul_f32_e32 v64, v64, v64
	v_mul_f32_e32 v65, v63, v65
	v_fma_f32 v63, -v63, v63, v64
	v_add_f32_e32 v64, v63, v63
	v_mul_f32_e32 v64, v65, v64
	v_mul_f32_e32 v65, v65, v65
	v_fma_f32 v63, v63, v63, -v65
	v_add_f32_e32 v65, v63, v63
	v_mul_f32_e32 v65, v64, v65
	v_mul_f32_e32 v64, v64, v64
	v_fma_f32 v63, v63, v63, -v64
	v_add_f32_e32 v64, v63, v63
	v_mul_f32_e32 v64, v65, v64
	v_mul_f32_e32 v65, v65, v65
	v_fma_f32 v63, v63, v63, -v65
	v_add_f32_e32 v65, v63, v63
	v_mul_f32_e32 v65, v64, v65
	v_mul_f32_e32 v64, v64, v64
	v_fma_f32 v63, v63, v63, -v64
	v_add_f32_e32 v64, v63, v63
	v_mul_f32_e32 v66, v65, v64
	v_mul_f32_e32 v64, v65, v65
	v_fma_f32 v63, v63, v63, -v64
	v_lshl_add_u32 v68, v62, 4, s1
	v_add_f32_e32 v64, v63, v63
	v_mul_f32_e32 v65, v66, v66
	v_ashrrev_i32_e32 v69, 31, v68
	v_mul_f32_e32 v64, v66, v64
	v_fma_f32 v66, v63, v63, -v65
	v_lshlrev_b64 v[68:69], 12, v[68:69]
	v_mov_b32_e32 v74, 0
	v_lshl_add_u64 v[68:69], v[58:59], 0, v[68:69]
	v_mov_b32_e32 v67, v66
	v_mov_b32_e32 v65, v64
	s_mov_b64 s[10:11], 0
	v_mov_b32_e32 v63, v78
	v_mov_b32_e32 v75, v74
	global_load_dwordx2 v[114:115], v[68:69], off
	global_load_dwordx2 v[116:117], v[68:69], off offset:512
	global_load_dwordx2 v[118:119], v[68:69], off offset:1024
	global_load_dwordx2 v[120:121], v[68:69], off offset:1536
	global_load_dwordx2 v[122:123], v[68:69], off offset:2048
	global_load_dwordx2 v[124:125], v[68:69], off offset:2560
	global_load_dwordx2 v[126:127], v[68:69], off offset:3072
	v_readfirstlane_b32 s98, v78
	v_pk_mul_f32 v[72:73], v[64:65], v[74:75] op_sel:[0,1] op_sel_hi:[1,0]
	s_nop 0
	v_pk_fma_f32 v[92:93], v[66:67], v[74:75], v[72:73] neg_lo:[0,0,1] neg_hi:[0,0,1]
	v_pk_fma_f32 v[72:73], v[66:67], v[74:75], v[72:73]
	s_nop 0
	v_mov_b32_e32 v93, v73
	s_waitcnt vmcnt(6)
	v_pk_add_f32 v[74:75], v[92:93], v[114:115]
	s_cmp_eq_u32 s98, 1
	s_cbranch_scc1 .Ls5b_prefix_done
	v_pk_mul_f32 v[72:73], v[64:65], v[74:75] op_sel:[0,1] op_sel_hi:[1,0]
	s_nop 0
	v_pk_fma_f32 v[92:93], v[66:67], v[74:75], v[72:73] neg_lo:[0,0,1] neg_hi:[0,0,1]
	v_pk_fma_f32 v[72:73], v[66:67], v[74:75], v[72:73]
	s_nop 0
	v_mov_b32_e32 v93, v73
	s_waitcnt vmcnt(5)
	v_pk_add_f32 v[74:75], v[92:93], v[116:117]
	s_cmp_eq_u32 s98, 2
	s_cbranch_scc1 .Ls5b_prefix_done
	v_pk_mul_f32 v[72:73], v[64:65], v[74:75] op_sel:[0,1] op_sel_hi:[1,0]
	s_nop 0
	v_pk_fma_f32 v[92:93], v[66:67], v[74:75], v[72:73] neg_lo:[0,0,1] neg_hi:[0,0,1]
	v_pk_fma_f32 v[72:73], v[66:67], v[74:75], v[72:73]
	s_nop 0
	v_mov_b32_e32 v93, v73
	s_waitcnt vmcnt(4)
	v_pk_add_f32 v[74:75], v[92:93], v[118:119]
	s_cmp_eq_u32 s98, 3
	s_cbranch_scc1 .Ls5b_prefix_done
	v_pk_mul_f32 v[72:73], v[64:65], v[74:75] op_sel:[0,1] op_sel_hi:[1,0]
	s_nop 0
	v_pk_fma_f32 v[92:93], v[66:67], v[74:75], v[72:73] neg_lo:[0,0,1] neg_hi:[0,0,1]
	v_pk_fma_f32 v[72:73], v[66:67], v[74:75], v[72:73]
	s_nop 0
	v_mov_b32_e32 v93, v73
	s_waitcnt vmcnt(3)
	v_pk_add_f32 v[74:75], v[92:93], v[120:121]
	s_cmp_eq_u32 s98, 4
	s_cbranch_scc1 .Ls5b_prefix_done
	v_pk_mul_f32 v[72:73], v[64:65], v[74:75] op_sel:[0,1] op_sel_hi:[1,0]
	s_nop 0
	v_pk_fma_f32 v[92:93], v[66:67], v[74:75], v[72:73] neg_lo:[0,0,1] neg_hi:[0,0,1]
	v_pk_fma_f32 v[72:73], v[66:67], v[74:75], v[72:73]
	s_nop 0
	v_mov_b32_e32 v93, v73
	s_waitcnt vmcnt(2)
	v_pk_add_f32 v[74:75], v[92:93], v[122:123]
	s_cmp_eq_u32 s98, 5
	s_cbranch_scc1 .Ls5b_prefix_done
	v_pk_mul_f32 v[72:73], v[64:65], v[74:75] op_sel:[0,1] op_sel_hi:[1,0]
	s_nop 0
	v_pk_fma_f32 v[92:93], v[66:67], v[74:75], v[72:73] neg_lo:[0,0,1] neg_hi:[0,0,1]
	v_pk_fma_f32 v[72:73], v[66:67], v[74:75], v[72:73]
	s_nop 0
	v_mov_b32_e32 v93, v73
	s_waitcnt vmcnt(1)
	v_pk_add_f32 v[74:75], v[92:93], v[124:125]
	s_cmp_eq_u32 s98, 6
	s_cbranch_scc1 .Ls5b_prefix_done
	v_pk_mul_f32 v[72:73], v[64:65], v[74:75] op_sel:[0,1] op_sel_hi:[1,0]
	s_nop 0
	v_pk_fma_f32 v[92:93], v[66:67], v[74:75], v[72:73] neg_lo:[0,0,1] neg_hi:[0,0,1]
	v_pk_fma_f32 v[72:73], v[66:67], v[74:75], v[72:73]
	s_nop 0
	v_mov_b32_e32 v93, v73
	s_waitcnt vmcnt(0)
	v_pk_add_f32 v[74:75], v[92:93], v[126:127]
; #define LAS __attribute__((address_space(3)))
; DI float lo16(unsigned u) { return __uint_as_float(u << 16); }
; DI float hi16(unsigned u) { return __uint_as_float(u & 0xffff0000u); }
; template <bool PASSB>
; DI void s5_pass(const int tid, LAS unsigned char* lds, const P& p, int G, int c0) {
;     ...
;             for (int s = 0; s < seg; ++s) { const float* he = hend + (((size_t)(b * 16 + g) * 8 + s) * 64 + lane) * 2; const float er = he[0], ei = he[1];
;                 const float nr = pr * hre - pi * him + er, ni = pr * him + pi * hre + ei; hre = nr; him = ni; }
;         }
;         const size_t tokbase = (size_t)b * SEQ + seg * 256;
;         for (int tile = 0; tile < 16; ++tile) {
;             if (lane < 32) { const int tk = lane >> 1, hf = lane & 1;
;                 const u32x4 raw = *(const u32x4*)(us5 + (tokbase + tile * 16 + tk) * 256 + g * 16 + hf * 8);
;                 LAS float* d = ubuf + tk * 16 + hf * 8;
;                 *(LAS f32x4*)d = (f32x4){lo16(raw.x), hi16(raw.x), lo16(raw.y), hi16(raw.y)}; *(LAS f32x4*)(d + 4) = (f32x4){lo16(raw.z), hi16(raw.z), lo16(raw.w), hi16(raw.w)}; }
.Ls5b_prefix_done:
	s_or_b64 exec, exec, s[10:11]
.LBB0_572:
	s_or_b64 exec, exec, s[8:9]
	v_ashrrev_i32_e32 v63, 31, v62
	s_ashr_i32 s1, s0, 31
	v_lshlrev_b64 v[62:63], 11, v[62:63]
	s_lshl_b64 s[0:1], s[0:1], 1
	v_or_b32_e32 v62, v62, v52
	v_lshl_add_u64 v[64:65], v[54:55], 0, s[0:1]
	v_lshl_add_u64 v[66:67], v[56:57], 0, s[0:1]
	v_mov_b32_e32 v112, v49
	v_mov_b32_e32 v113, 0
	v_lshl_add_u64 v[112:113], v[62:63], 0, v[112:113]
	v_lshlrev_b64 v[112:113], 9, v[112:113]
	v_lshl_add_u64 v[112:113], v[64:65], 0, v[112:113]
	global_load_dwordx4 v[108:111], v[112:113], off
	s_waitcnt vmcnt(0)
	v_mov_b32_e32 v68, v3
	s_waitcnt vmcnt(9)
	v_mov_b32_e32 v69, v47
	v_mov_b32_e32 v3, v46
	v_mov_b32_e32 v46, v1
	v_mov_b32_e32 v47, v45
	v_mov_b32_e32 v1, v44
	v_mov_b32_e32 v44, v7
	s_waitcnt vmcnt(8)
	v_mov_b32_e32 v45, v43
	v_mov_b32_e32 v7, v42
	v_mov_b32_e32 v42, v5
	v_mov_b32_e32 v43, v41
	v_mov_b32_e32 v5, v40
	v_mov_b32_e32 v40, v11
	s_waitcnt vmcnt(7)
	v_mov_b32_e32 v41, v35
	v_mov_b32_e32 v70, v9
	v_mov_b32_e32 v71, v33
	v_mov_b32_e32 v9, v32
	v_mov_b32_e32 v72, v15
	s_waitcnt vmcnt(6)
	v_mov_b32_e32 v73, v39
	v_mov_b32_e32 v15, v38
	v_mov_b32_e32 v38, v13
	v_mov_b32_e32 v39, v37
	v_mov_b32_e32 v13, v36
	v_mov_b32_e32 v11, v34
	s_waitcnt vmcnt(5)
	v_pk_mov_b32 v[36:37], v[60:61], v[60:61] op_sel:[1,0]
	s_mov_b32 s8, 0
